# conversion schedule rebalanced: wa/wb/wo of both layers converted in the in-proj idle slots (P0 keeps only w_in L0 + x), table-driven two-in-flight slot routine
# baseline (speedup 1.0000x reference)
;     ...
;     for (int mi = 0; mi < 7 * DEPTH; ++mi) {
;         if (!((mask >> mi) & 1u)) continue;
;         const int l = mi / 7, kind = mi - 7 * l;
;         const float* W; const float* ks = nullptr; bf16_t* WT; int K, N, rm = 0;
; __global__ void __launch_bounds__(NTHREADS, 2) mk_fwd(Args args) {
;     ...
;     if (KON(0) && IN(0)) { const int vcu = (G % 8 == 0) ? (blk % 8) * (G / 8) + blk / 8 : blk; p0_prologue(args, vcu * NWAVES + wave, G * NWAVES, lane, 0x000Fu | 0x0010u | 0x0800u, true, 0x0810u, 0, 10); }
.LBB0_11:
	s_lshl_b32 s48, 1, s43
	s_cmpk_eq_u32 s3, 0x100
	s_cselect_b32 s4, 1, 0x81f
	s_and_b32 s4, s48, s4
	s_cmp_eq_u32 s4, 0
	s_cbranch_scc1 .LBB0_10
	s_cmp_gt_u32 s43, 6
	s_cselect_b64 s[18:19], -1, 0
	s_and_b64 s[4:5], s[18:19], exec
	s_cselect_b32 s49, -7, 0
	s_add_i32 s49, s49, s43
	s_mov_b64 s[24:25], -1
	s_mov_b64 s[22:23], 0
	s_cmp_lt_i32 s49, 3
	s_mov_b64 s[20:21], 0
	s_cbranch_scc0 .LBB0_31
	s_movk_i32 s47, 0x800
	s_and_b64 vcc, exec, s[24:25]
	s_cbranch_vccnz .LBB0_43

;     ...
;     for (int mi = 0; mi < 7 * DEPTH; ++mi) {
;         if (!((mask >> mi) & 1u)) continue;
;         const int l = mi / 7, kind = mi - 7 * l;
;         const float* W; const float* ks = nullptr; bf16_t* WT; int K, N, rm = 0;
;         if (kind == 0)      { W = a.in[2] + (size_t)l * 2048 * 7680;  K = 2048; N = 7680; WT = (bf16_t*)(ws + WS_WIN + l * SZ_WIN); ks = a.in[1] + l * 2048; rm = 3; }
;         else if (kind == 1) { W = a.in[10] + (size_t)l * 1024 * 2048; K = 1024; N = 2048; WT = (bf16_t*)(ws + WS_WA + l * SZ_WA); }
;         else if (kind == 2) { W = a.in[11] + (size_t)l * 1024 * 2048; K = 1024; N = 2048; WT = (bf16_t*)(ws + WS_WB + l * SZ_WB); }
;         else if (kind == 3) { W = a.in[12] + (size_t)l * 2048 * 2048; K = 2048; N = 2048; WT = (bf16_t*)(ws + WS_WO + l * SZ_WO); }
;         else if (kind == 4) { W = a.in[14] + (size_t)l * 2048 * 5632; K = 2048; N = 5632; WT = (bf16_t*)(ws + WS_WGU + l * SZ_WGU); ks = a.in[13] + l * 2048; rm = 1; }
;         else if (kind == 5) { W = a.in[15] + (size_t)l * 2048 * 5632; K = 2048; N = 5632; WT = (bf16_t*)(ws + WS_WGU + l * SZ_WGU); ks = a.in[13] + l * 2048; rm = 2; }
;         else                { W = a.in[16] + (size_t)l * 5632 * 2048; K = 5632; N = 2048; WT = (bf16_t*)(ws + WS_WD + l * SZ_WD); }
;         const int nitems = (K >> 6) * (N >> 5);
;         int ilo = 0, ihi = nitems; if ((fmask >> mi) & 1u) { ilo = (nitems * flo) >> 4; ihi = (nitems * fhi) >> 4; }
;         const int cnt = ihi - ilo;
;         int first = (gw - base) % NGW; if (first < 0) first += NGW;
;         for (int it = first; it < cnt; it += NGW) tr_item(W, K, N, WT, ks, rm, ilo + it, lane);
;         base = (base + cnt) % NGW;
.LBB0_208:
	v_readlane_b32 s16, v248, 37
	v_readlane_b32 s17, v248, 38
	s_andn2_b64 vcc, exec, s[16:17]
	s_cbranch_vccnz .LBB0_256
	s_cmpk_lg_u32 s3, 0x100
	s_cbranch_scc1 .Lslot_in_orig
	v_readfirstlane_b32 s2, v204
	v_and_b32_e32 v43, 63, v204
	v_lshrrev_b32_e32 v102, 3, v43
	v_and_b32_e32 v103, 7, v43
	s_lshr_b32 s2, s2, 6
	s_sub_i32 s19, s85, 192
	s_lshl_b32 s19, s19, 3
	s_add_i32 s2, s2, s19
	v_lshlrev_b32_e32 v110, 5, v102
	s_mov_b32 s28, 0
	s_cmp_lg_u32 s64, 0
	s_cselect_b32 s28, 16, 0
.Lsl_in_dispatch:
	s_cmp_eq_u32 s28, 0
	s_cbranch_scc1 .Lsl_in_set0
	s_cmp_eq_u32 s28, 1
	s_cbranch_scc1 .Lsl_in_set1
	s_cmp_eq_u32 s28, 2
	s_cbranch_scc1 .Lsl_in_set2
	s_cmp_eq_u32 s28, 3
	s_cbranch_scc1 .Lsl_in_set3
	s_cmp_eq_u32 s28, 4
	s_cbranch_scc1 .Lsl_in_set4
	s_cmp_eq_u32 s28, 16
	s_cbranch_scc1 .Lsl_in_set16
	s_cmp_eq_u32 s28, 17
	s_cbranch_scc1 .Lsl_in_set17
	s_cmp_eq_u32 s28, 18
	s_cbranch_scc1 .Lsl_in_set18
	s_cmp_eq_u32 s28, 19
	s_cbranch_scc1 .Lsl_in_set19
	s_cmp_eq_u32 s28, 20
	s_cbranch_scc1 .Lsl_in_set20
	s_branch .LBB0_256
.Lsl_in_set0:
	v_readlane_b32 s22, v250, 30
	v_readlane_b32 s23, v250, 31
	v_readlane_b32 s24, v250, 36
	v_readlane_b32 s25, v250, 37
	v_readlane_b32 s26, v250, 28
	v_readlane_b32 s27, v250, 29
	v_mul_u32_u24_e32 v104, 0x2c000, v102
	v_lshl_add_u32 v104, v103, 4, v104
	v_mul_u32_u24_e32 v105, 0x4000, v103
	v_lshl_add_u32 v105, v102, 4, v105
	s_add_u32 s24, s24, 0x5dc0000
	s_addc_u32 s25, s25, 0
	s_mov_b32 s36, 0x5800
	s_mov_b32 s37, 0x160000
	s_movk_i32 s38, 2979
	s_mov_b32 s39, 19
	s_movk_i32 s40, 176
	s_movk_i32 s41, 0x1000
	s_mov_b32 s42, 1
	s_mov_b32 s43, 1
	s_movk_i32 s44, 3520
	s_movk_i32 s29, 2112
	s_sub_i32 s4, s2, 0
	s_and_b32 s4, s4, 511
	s_branch .Lsl_in_loop
.Lsl_in_set1:
	v_readlane_b32 s22, v250, 32
	v_readlane_b32 s23, v250, 33
	v_readlane_b32 s24, v250, 36
	v_readlane_b32 s25, v250, 37
	v_readlane_b32 s26, v250, 28
	v_readlane_b32 s27, v250, 29
	v_mul_u32_u24_e32 v104, 0x2c000, v102
	v_lshl_add_u32 v104, v103, 4, v104
	v_mul_u32_u24_e32 v105, 0x4000, v103
	v_lshl_add_u32 v105, v102, 4, v105
	s_add_u32 s24, s24, 0x5dc0000
	s_addc_u32 s25, s25, 0
	s_mov_b32 s36, 0x5800
	s_mov_b32 s37, 0x160000
	s_movk_i32 s38, 2979
	s_mov_b32 s39, 19
	s_movk_i32 s40, 176
	s_movk_i32 s41, 0x1000
	s_mov_b32 s42, 2
	s_mov_b32 s43, 1
	s_movk_i32 s44, 0
	s_movk_i32 s29, 5632
	s_sub_i32 s4, s2, 64
	s_and_b32 s4, s4, 511
	s_branch .Lsl_in_loop
.Lsl_in_set2:
	v_readlane_b32 s22, v250, 22
	v_readlane_b32 s23, v250, 23
	v_readlane_b32 s24, v250, 36
	v_readlane_b32 s25, v250, 37
	v_mul_u32_u24_e32 v104, 0x10000, v102
	v_lshl_add_u32 v104, v103, 4, v104
	v_mul_u32_u24_e32 v105, 0x2000, v103
	v_lshl_add_u32 v105, v102, 4, v105
	s_add_u32 s24, s24, 0x3dc0000
	s_addc_u32 s25, s25, 0
	s_mov_b32 s36, 0x2000
	s_mov_b32 s37, 0x80000
	s_movk_i32 s38, 1
	s_mov_b32 s39, 6
	s_movk_i32 s40, 64
	s_movk_i32 s41, 0x800
	s_mov_b32 s42, 0
	s_mov_b32 s43, 0
	s_movk_i32 s44, 0
	s_movk_i32 s29, 1024
	s_sub_i32 s4, s2, 64
	s_and_b32 s4, s4, 511
	s_branch .Lsl_in_loop
.Lsl_in_set3:
	v_readlane_b32 s22, v250, 24
	v_readlane_b32 s23, v250, 25
	v_readlane_b32 s24, v250, 36
	v_readlane_b32 s25, v250, 37
	v_mul_u32_u24_e32 v104, 0x10000, v102
	v_lshl_add_u32 v104, v103, 4, v104
	v_mul_u32_u24_e32 v105, 0x2000, v103
	v_lshl_add_u32 v105, v102, 4, v105
	s_add_u32 s24, s24, 0x45c0000
	s_addc_u32 s25, s25, 0
	s_mov_b32 s36, 0x2000
	s_mov_b32 s37, 0x80000
	s_movk_i32 s38, 1
	s_mov_b32 s39, 6
	s_movk_i32 s40, 64
	s_movk_i32 s41, 0x800
	s_mov_b32 s42, 0
	s_mov_b32 s43, 0
	s_movk_i32 s44, 0
	s_movk_i32 s29, 1024
	s_sub_i32 s4, s2, 64
	s_and_b32 s4, s4, 511
	s_branch .Lsl_in_loop
.Lsl_in_set4:
	v_readlane_b32 s22, v250, 26
	v_readlane_b32 s23, v250, 27
	v_readlane_b32 s24, v250, 36
	v_readlane_b32 s25, v250, 37
	v_mul_u32_u24_e32 v104, 0x10000, v102
	v_lshl_add_u32 v104, v103, 4, v104
	v_mul_u32_u24_e32 v105, 0x4000, v103
	v_lshl_add_u32 v105, v102, 4, v105
	s_add_u32 s24, s24, 0x4dc0000
	s_addc_u32 s25, s25, 0
	s_mov_b32 s36, 0x2000
	s_mov_b32 s37, 0x80000
	s_movk_i32 s38, 1
	s_mov_b32 s39, 6
	s_movk_i32 s40, 64
	s_movk_i32 s41, 0x1000
	s_mov_b32 s42, 0
	s_mov_b32 s43, 0
	s_movk_i32 s44, 0
	s_movk_i32 s29, 2048
	s_sub_i32 s4, s2, 64
	s_and_b32 s4, s4, 511
	s_branch .Lsl_in_loop
.Lsl_in_set16:
	v_readlane_b32 s22, v250, 30
	v_readlane_b32 s23, v250, 31
	v_readlane_b32 s24, v250, 36
	v_readlane_b32 s25, v250, 37
	v_readlane_b32 s26, v250, 28
	v_readlane_b32 s27, v250, 29
	v_mul_u32_u24_e32 v104, 0x2c000, v102
	v_lshl_add_u32 v104, v103, 4, v104
	v_mul_u32_u24_e32 v105, 0x4000, v103
	v_lshl_add_u32 v105, v102, 4, v105
	s_add_u32 s22, s22, 0x2c00000
	s_addc_u32 s23, s23, 0
	s_add_u32 s24, s24, 0x89c0000
	s_addc_u32 s25, s25, 0
	s_add_u32 s26, s26, 0x2000
	s_addc_u32 s27, s27, 0
	s_mov_b32 s36, 0x5800
	s_mov_b32 s37, 0x160000
	s_movk_i32 s38, 2979
	s_mov_b32 s39, 19
	s_movk_i32 s40, 176
	s_movk_i32 s41, 0x1000
	s_mov_b32 s42, 1
	s_mov_b32 s43, 1
	s_movk_i32 s44, 3520
	s_movk_i32 s29, 2112
	s_sub_i32 s4, s2, 0
	s_and_b32 s4, s4, 511
	s_branch .Lsl_in_loop
.Lsl_in_set17:
	v_readlane_b32 s22, v250, 32
	v_readlane_b32 s23, v250, 33
	v_readlane_b32 s24, v250, 36
	v_readlane_b32 s25, v250, 37
	v_readlane_b32 s26, v250, 28
	v_readlane_b32 s27, v250, 29
	v_mul_u32_u24_e32 v104, 0x2c000, v102
	v_lshl_add_u32 v104, v103, 4, v104
	v_mul_u32_u24_e32 v105, 0x4000, v103
	v_lshl_add_u32 v105, v102, 4, v105
	s_add_u32 s22, s22, 0x2c00000
	s_addc_u32 s23, s23, 0
	s_add_u32 s24, s24, 0x89c0000
	s_addc_u32 s25, s25, 0
	s_add_u32 s26, s26, 0x2000
	s_addc_u32 s27, s27, 0
	s_mov_b32 s36, 0x5800
	s_mov_b32 s37, 0x160000
	s_movk_i32 s38, 2979
	s_mov_b32 s39, 19
	s_movk_i32 s40, 176
	s_movk_i32 s41, 0x1000
	s_mov_b32 s42, 2
	s_mov_b32 s43, 1
	s_movk_i32 s44, 0
	s_movk_i32 s29, 5632
	s_sub_i32 s4, s2, 64
	s_and_b32 s4, s4, 511
	s_branch .Lsl_in_loop
; __device__ __forceinline__ unsigned cvt_pk_bf16(float lo, float hi) { unsigned r; asm volatile("v_cvt_pk_bf16_f32 %0, %1, %2" : "=v"(r) : "v"(lo), "v"(hi)); return r; }
; __device__ __forceinline__ void st16_wt(void* p, u32x4 v) { asm volatile("global_store_dwordx4 %0, %1, off sc1\n\ts_nop 1" :: "v"(p), "v"(v) : "memory"); }
; __device__ __forceinline__ void tr_item(const float* __restrict__ W, int K, int N, bf16_t* WT, const float* __restrict__ kscale, int rowmode, int item, int lane) {
;     const int nblk = N >> 5, kb = item / nblk, nb = item - kb * nblk;
;     const int c = lane >> 3, q = lane & 7, k0 = kb * 64 + c * 8, n0 = nb * 32 + q * 4;
;     f32x4 v[8];
; #pragma unroll
;     for (int i = 0; i < 8; ++i) v[i] = __builtin_nontemporal_load((const f32x4*)(W + (size_t)(k0 + i) * N + n0));
;     if (kscale) { const f32x4 s0 = *(const f32x4*)(kscale + k0), s1 = *(const f32x4*)(kscale + k0 + 4);
; #pragma unroll
;         for (int i = 0; i < 4; ++i) { v[i] = v[i] * s0[i]; v[4 + i] = v[4 + i] * s1[i]; } }
;     int drow;
;     if (rowmode == 0) drow = n0;
;     else if (rowmode == 3) { const int g = n0 - pg8::C_GA; drow = g < 0 ? n0 : pg8::C_GA + (((g & 2047) >> 7) << 8) + ((g >> 11) << 7) + (g & 127); }
;     else drow = ((n0 >> 7) << 8) + (n0 & 127) + (rowmode == 2 ? 128 : 0);
; #pragma unroll
;     for (int e = 0; e < 4; ++e) { u32x4 o; o.x = cvt_pk_bf16(v[0][e], v[1][e]); o.y = cvt_pk_bf16(v[2][e], v[3][e]); o.z = cvt_pk_bf16(v[4][e], v[5][e]); o.w = cvt_pk_bf16(v[6][e], v[7][e]);
;         pg8::st16_wt(WT + (size_t)(drow + e) * K + k0, o); }
.Lsl_in_set18:
	v_readlane_b32 s22, v250, 22
	v_readlane_b32 s23, v250, 23
	v_readlane_b32 s24, v250, 36
	v_readlane_b32 s25, v250, 37
	v_mul_u32_u24_e32 v104, 0x10000, v102
	v_lshl_add_u32 v104, v103, 4, v104
	v_mul_u32_u24_e32 v105, 0x2000, v103
	v_lshl_add_u32 v105, v102, 4, v105
	s_add_u32 s22, s22, 0x800000
	s_addc_u32 s23, s23, 0
	s_add_u32 s24, s24, 0x41c0000
	s_addc_u32 s25, s25, 0
	s_mov_b32 s36, 0x2000
	s_mov_b32 s37, 0x80000
	s_movk_i32 s38, 1
	s_mov_b32 s39, 6
	s_movk_i32 s40, 64
	s_movk_i32 s41, 0x800
	s_mov_b32 s42, 0
	s_mov_b32 s43, 0
	s_movk_i32 s44, 0
	s_movk_i32 s29, 1024
	s_sub_i32 s4, s2, 64
	s_and_b32 s4, s4, 511
	s_branch .Lsl_in_loop
.Lsl_in_set19:
	v_readlane_b32 s22, v250, 24
	v_readlane_b32 s23, v250, 25
	v_readlane_b32 s24, v250, 36
	v_readlane_b32 s25, v250, 37
	v_mul_u32_u24_e32 v104, 0x10000, v102
	v_lshl_add_u32 v104, v103, 4, v104
	v_mul_u32_u24_e32 v105, 0x2000, v103
	v_lshl_add_u32 v105, v102, 4, v105
	s_add_u32 s22, s22, 0x800000
	s_addc_u32 s23, s23, 0
	s_add_u32 s24, s24, 0x49c0000
	s_addc_u32 s25, s25, 0
	s_mov_b32 s36, 0x2000
	s_mov_b32 s37, 0x80000
	s_movk_i32 s38, 1
	s_mov_b32 s39, 6
	s_movk_i32 s40, 64
	s_movk_i32 s41, 0x800
	s_mov_b32 s42, 0
	s_mov_b32 s43, 0
	s_movk_i32 s44, 0
	s_movk_i32 s29, 1024
	s_sub_i32 s4, s2, 64
	s_and_b32 s4, s4, 511
	s_branch .Lsl_in_loop
.Lsl_in_set20:
	v_readlane_b32 s22, v250, 26
	v_readlane_b32 s23, v250, 27
	v_readlane_b32 s24, v250, 36
	v_readlane_b32 s25, v250, 37
	v_mul_u32_u24_e32 v104, 0x10000, v102
	v_lshl_add_u32 v104, v103, 4, v104
	v_mul_u32_u24_e32 v105, 0x4000, v103
	v_lshl_add_u32 v105, v102, 4, v105
	s_add_u32 s22, s22, 0x1000000
	s_addc_u32 s23, s23, 0
	s_add_u32 s24, s24, 0x55c0000
	s_addc_u32 s25, s25, 0
	s_mov_b32 s36, 0x2000
	s_mov_b32 s37, 0x80000
	s_movk_i32 s38, 1
	s_mov_b32 s39, 6
	s_movk_i32 s40, 64
	s_movk_i32 s41, 0x1000
	s_mov_b32 s42, 0
	s_mov_b32 s43, 0
	s_movk_i32 s44, 0
	s_movk_i32 s29, 2048
	s_sub_i32 s4, s2, 64
	s_and_b32 s4, s4, 511
	s_branch .Lsl_in_loop
.Lsl_in_loop:
	s_cmp_ge_u32 s4, s29
	s_cbranch_scc1 .Lsl_in_next
	s_add_i32 s16, s4, s44
	s_mul_i32 s17, s16, s38
	s_lshr_b32 s17, s17, s39
	s_mul_i32 s19, s17, s40
	s_sub_i32 s18, s16, s19
	s_mul_i32 s19, s17, s37
	s_lshl_b32 s20, s18, 7
	s_add_i32 s19, s19, s20
	v_add_u32_e32 v42, s19, v104
	s_cmp_eq_u32 s43, 0
	s_cbranch_scc1 .Lsl_in_nks1
	s_lshl_b32 s19, s17, 8
	v_add_u32_e32 v43, s19, v110
	global_load_dwordx4 v[34:37], v43, s[26:27]
	global_load_dwordx4 v[38:41], v43, s[26:27] offset:16
.Lsl_in_nks1:
	global_load_dwordx4 v[2:5], v42, s[22:23] nt
	v_add_u32_e32 v42, s36, v42
	global_load_dwordx4 v[6:9], v42, s[22:23] nt
	v_add_u32_e32 v42, s36, v42
	global_load_dwordx4 v[10:13], v42, s[22:23] nt
	v_add_u32_e32 v42, s36, v42
	global_load_dwordx4 v[14:17], v42, s[22:23] nt
	v_add_u32_e32 v42, s36, v42
	global_load_dwordx4 v[18:21], v42, s[22:23] nt
	v_add_u32_e32 v42, s36, v42
	global_load_dwordx4 v[22:25], v42, s[22:23] nt
	v_add_u32_e32 v42, s36, v42
	global_load_dwordx4 v[26:29], v42, s[22:23] nt
	v_add_u32_e32 v42, s36, v42
	global_load_dwordx4 v[30:33], v42, s[22:23] nt
	s_lshl_b32 s19, s18, 5
	s_cmp_eq_u32 s42, 0
	s_cbranch_scc1 .Lsl_in_rmd2
	s_cmp_eq_u32 s42, 3
	s_cbranch_scc1 .Lsl_in_rm33
	s_lshr_b32 s20, s19, 7
	s_lshl_b32 s20, s20, 8
	s_and_b32 s19, s19, 0x7f
	s_add_i32 s19, s19, s20
	s_and_b32 s20, s42, 2
	s_lshl_b32 s20, s20, 6
	s_add_i32 s19, s19, s20
	s_branch .Lsl_in_rmd2
.Lsl_in_rm33:
	s_cmp_lt_u32 s19, 0xe00
	s_cbranch_scc1 .Lsl_in_rmd2
	s_sub_i32 s19, s19, 0xe00
	s_and_b32 s20, s19, 0x7ff
	s_lshr_b32 s20, s20, 7
	s_lshl_b32 s20, s20, 8
	s_lshr_b32 s21, s19, 11
	s_lshl_b32 s21, s21, 7
	s_and_b32 s19, s19, 0x7f
	s_add_i32 s19, s19, s20
	s_add_i32 s19, s19, s21
	s_add_i32 s19, s19, 0xe00
.Lsl_in_rmd2:
	s_mul_i32 s19, s19, s41
	s_lshl_b32 s20, s17, 7
	s_add_i32 s19, s19, s20
	v_add_u32_e32 v44, s19, v105
	s_add_i32 s4, s4, 512
	s_cmp_ge_u32 s4, s29
	s_cbranch_scc1 .Lsl_in_single
	s_add_i32 s16, s4, s44
	s_mul_i32 s17, s16, s38
	s_lshr_b32 s17, s17, s39
	s_mul_i32 s19, s17, s40
	s_sub_i32 s18, s16, s19
	s_mul_i32 s19, s17, s37
	s_lshl_b32 s20, s18, 7
	s_add_i32 s19, s19, s20
	v_add_u32_e32 v42, s19, v104
	s_cmp_eq_u32 s43, 0
	s_cbranch_scc1 .Lsl_in_nks4
	s_lshl_b32 s19, s17, 8
	v_add_u32_e32 v43, s19, v110
	global_load_dwordx4 v[78:81], v43, s[26:27]
	global_load_dwordx4 v[82:85], v43, s[26:27] offset:16
.Lsl_in_nks4:
	global_load_dwordx4 v[46:49], v42, s[22:23] nt
	v_add_u32_e32 v42, s36, v42
	global_load_dwordx4 v[50:53], v42, s[22:23] nt
	v_add_u32_e32 v42, s36, v42
	global_load_dwordx4 v[54:57], v42, s[22:23] nt
	v_add_u32_e32 v42, s36, v42
	global_load_dwordx4 v[58:61], v42, s[22:23] nt
	v_add_u32_e32 v42, s36, v42
	global_load_dwordx4 v[62:65], v42, s[22:23] nt
	v_add_u32_e32 v42, s36, v42
	global_load_dwordx4 v[66:69], v42, s[22:23] nt
	v_add_u32_e32 v42, s36, v42
	global_load_dwordx4 v[70:73], v42, s[22:23] nt
	v_add_u32_e32 v42, s36, v42
	global_load_dwordx4 v[74:77], v42, s[22:23] nt
	s_lshl_b32 s19, s18, 5
	s_cmp_eq_u32 s42, 0
	s_cbranch_scc1 .Lsl_in_rmd5
	s_cmp_eq_u32 s42, 3
	s_cbranch_scc1 .Lsl_in_rm36
	s_lshr_b32 s20, s19, 7
	s_lshl_b32 s20, s20, 8
	s_and_b32 s19, s19, 0x7f
	s_add_i32 s19, s19, s20
	s_and_b32 s20, s42, 2
	s_lshl_b32 s20, s20, 6
	s_add_i32 s19, s19, s20
	s_branch .Lsl_in_rmd5

; __device__ __forceinline__ unsigned cvt_pk_bf16(float lo, float hi) { unsigned r; asm volatile("v_cvt_pk_bf16_f32 %0, %1, %2" : "=v"(r) : "v"(lo), "v"(hi)); return r; }
; __device__ __forceinline__ void st16_wt(void* p, u32x4 v) { asm volatile("global_store_dwordx4 %0, %1, off sc1\n\ts_nop 1" :: "v"(p), "v"(v) : "memory"); }
; __device__ __forceinline__ void tr_item(const float* __restrict__ W, int K, int N, bf16_t* WT, const float* __restrict__ kscale, int rowmode, int item, int lane) {
;     ...
;     int drow;
;     if (rowmode == 0) drow = n0;
;     else if (rowmode == 3) { const int g = n0 - pg8::C_GA; drow = g < 0 ? n0 : pg8::C_GA + (((g & 2047) >> 7) << 8) + ((g >> 11) << 7) + (g & 127); }
;     else drow = ((n0 >> 7) << 8) + (n0 & 127) + (rowmode == 2 ? 128 : 0);
; #pragma unroll
;     for (int e = 0; e < 4; ++e) { u32x4 o; o.x = cvt_pk_bf16(v[0][e], v[1][e]); o.y = cvt_pk_bf16(v[2][e], v[3][e]); o.z = cvt_pk_bf16(v[4][e], v[5][e]); o.w = cvt_pk_bf16(v[6][e], v[7][e]);
;         pg8::st16_wt(WT + (size_t)(drow + e) * K + k0, o); }
.Lsl_in_rmd5:
	s_mul_i32 s19, s19, s41
	s_lshl_b32 s20, s17, 7
	s_add_i32 s19, s19, s20
	v_add_u32_e32 v45, s19, v105
	s_add_i32 s4, s4, 512
	s_cmp_eq_u32 s43, 0
	s_cbranch_scc1 .Lsl_in_w87
	s_waitcnt vmcnt(10)
	s_branch .Lsl_in_wd8

; __device__ __forceinline__ unsigned cvt_pk_bf16(float lo, float hi) { unsigned r; asm volatile("v_cvt_pk_bf16_f32 %0, %1, %2" : "=v"(r) : "v"(lo), "v"(hi)); return r; }
; __device__ __forceinline__ void st16_wt(void* p, u32x4 v) { asm volatile("global_store_dwordx4 %0, %1, off sc1\n\ts_nop 1" :: "v"(p), "v"(v) : "memory"); }
; __device__ __forceinline__ void tr_item(const float* __restrict__ W, int K, int N, bf16_t* WT, const float* __restrict__ kscale, int rowmode, int item, int lane) {
;     ...
;     if (kscale) { const f32x4 s0 = *(const f32x4*)(kscale + k0), s1 = *(const f32x4*)(kscale + k0 + 4);
; #pragma unroll
;         for (int i = 0; i < 4; ++i) { v[i] = v[i] * s0[i]; v[4 + i] = v[4 + i] * s1[i]; } }
;     int drow;
;     if (rowmode == 0) drow = n0;
;     else if (rowmode == 3) { const int g = n0 - pg8::C_GA; drow = g < 0 ? n0 : pg8::C_GA + (((g & 2047) >> 7) << 8) + ((g >> 11) << 7) + (g & 127); }
;     else drow = ((n0 >> 7) << 8) + (n0 & 127) + (rowmode == 2 ? 128 : 0);
; #pragma unroll
;     for (int e = 0; e < 4; ++e) { u32x4 o; o.x = cvt_pk_bf16(v[0][e], v[1][e]); o.y = cvt_pk_bf16(v[2][e], v[3][e]); o.z = cvt_pk_bf16(v[4][e], v[5][e]); o.w = cvt_pk_bf16(v[6][e], v[7][e]);
;         pg8::st16_wt(WT + (size_t)(drow + e) * K + k0, o); }
;     ...
;         int ilo = 0, ihi = nitems; if ((fmask >> mi) & 1u) { ilo = (nitems * flo) >> 4; ihi = (nitems * fhi) >> 4; }
;         const int cnt = ihi - ilo;
;         int first = (gw - base) % NGW; if (first < 0) first += NGW;
;         for (int it = first; it < cnt; it += NGW) tr_item(W, K, N, WT, ks, rm, ilo + it, lane);
;         base = (base + cnt) % NGW;
.Lsl_in_wd8:
	s_cmp_eq_u32 s43, 0
	s_cbranch_scc1 .Lsl_in_nmul9
	v_mul_f32_e32 v2, v2, v34
	v_mul_f32_e32 v3, v3, v34
	v_mul_f32_e32 v4, v4, v34
	v_mul_f32_e32 v5, v5, v34
	v_mul_f32_e32 v6, v6, v35
	v_mul_f32_e32 v7, v7, v35
	v_mul_f32_e32 v8, v8, v35
	v_mul_f32_e32 v9, v9, v35
	v_mul_f32_e32 v10, v10, v36
	v_mul_f32_e32 v11, v11, v36
	v_mul_f32_e32 v12, v12, v36
	v_mul_f32_e32 v13, v13, v36
	v_mul_f32_e32 v14, v14, v37
	v_mul_f32_e32 v15, v15, v37
	v_mul_f32_e32 v16, v16, v37
	v_mul_f32_e32 v17, v17, v37
	v_mul_f32_e32 v18, v18, v38
	v_mul_f32_e32 v19, v19, v38
	v_mul_f32_e32 v20, v20, v38
	v_mul_f32_e32 v21, v21, v38
	v_mul_f32_e32 v22, v22, v39
	v_mul_f32_e32 v23, v23, v39
	v_mul_f32_e32 v24, v24, v39
	v_mul_f32_e32 v25, v25, v39
	v_mul_f32_e32 v26, v26, v40
	v_mul_f32_e32 v27, v27, v40
	v_mul_f32_e32 v28, v28, v40
	v_mul_f32_e32 v29, v29, v40
	v_mul_f32_e32 v30, v30, v41
	v_mul_f32_e32 v31, v31, v41
	v_mul_f32_e32 v32, v32, v41
	v_mul_f32_e32 v33, v33, v41
.Lsl_in_nmul9:
	v_cvt_pk_bf16_f32 v86, v2, v6
	v_cvt_pk_bf16_f32 v87, v10, v14
	v_cvt_pk_bf16_f32 v88, v18, v22
	v_cvt_pk_bf16_f32 v89, v26, v30
	v_cvt_pk_bf16_f32 v90, v3, v7
	v_cvt_pk_bf16_f32 v91, v11, v15
	v_cvt_pk_bf16_f32 v92, v19, v23
	v_cvt_pk_bf16_f32 v93, v27, v31
	v_cvt_pk_bf16_f32 v94, v4, v8
	v_cvt_pk_bf16_f32 v95, v12, v16
	v_cvt_pk_bf16_f32 v96, v20, v24
	v_cvt_pk_bf16_f32 v97, v28, v32
	v_cvt_pk_bf16_f32 v98, v5, v9
	v_cvt_pk_bf16_f32 v99, v13, v17
	v_cvt_pk_bf16_f32 v100, v21, v25
	v_cvt_pk_bf16_f32 v101, v29, v33
	global_store_dwordx4 v44, v[86:89], s[24:25] sc1
	v_add_u32_e32 v44, s41, v44
	global_store_dwordx4 v44, v[90:93], s[24:25] sc1
	v_add_u32_e32 v44, s41, v44
	global_store_dwordx4 v44, v[94:97], s[24:25] sc1
	v_add_u32_e32 v44, s41, v44
	global_store_dwordx4 v44, v[98:101], s[24:25] sc1
	s_waitcnt vmcnt(4)
	s_cmp_eq_u32 s43, 0
	s_cbranch_scc1 .Lsl_in_nmul10
	v_mul_f32_e32 v46, v46, v78
	v_mul_f32_e32 v47, v47, v78
	v_mul_f32_e32 v48, v48, v78
	v_mul_f32_e32 v49, v49, v78
	v_mul_f32_e32 v50, v50, v79
	v_mul_f32_e32 v51, v51, v79
	v_mul_f32_e32 v52, v52, v79
	v_mul_f32_e32 v53, v53, v79
	v_mul_f32_e32 v54, v54, v80
	v_mul_f32_e32 v55, v55, v80
	v_mul_f32_e32 v56, v56, v80
	v_mul_f32_e32 v57, v57, v80
	v_mul_f32_e32 v58, v58, v81
	v_mul_f32_e32 v59, v59, v81
	v_mul_f32_e32 v60, v60, v81
	v_mul_f32_e32 v61, v61, v81
	v_mul_f32_e32 v62, v62, v82
	v_mul_f32_e32 v63, v63, v82
	v_mul_f32_e32 v64, v64, v82
	v_mul_f32_e32 v65, v65, v82
	v_mul_f32_e32 v66, v66, v83
	v_mul_f32_e32 v67, v67, v83
	v_mul_f32_e32 v68, v68, v83
	v_mul_f32_e32 v69, v69, v83
	v_mul_f32_e32 v70, v70, v84
	v_mul_f32_e32 v71, v71, v84
	v_mul_f32_e32 v72, v72, v84
	v_mul_f32_e32 v73, v73, v84
	v_mul_f32_e32 v74, v74, v85
	v_mul_f32_e32 v75, v75, v85
	v_mul_f32_e32 v76, v76, v85
	v_mul_f32_e32 v77, v77, v85
.Lsl_in_nmul10:
	v_cvt_pk_bf16_f32 v86, v46, v50
	v_cvt_pk_bf16_f32 v87, v54, v58
	v_cvt_pk_bf16_f32 v88, v62, v66
	v_cvt_pk_bf16_f32 v89, v70, v74
	v_cvt_pk_bf16_f32 v90, v47, v51
	v_cvt_pk_bf16_f32 v91, v55, v59
	v_cvt_pk_bf16_f32 v92, v63, v67
	v_cvt_pk_bf16_f32 v93, v71, v75
	v_cvt_pk_bf16_f32 v94, v48, v52
	v_cvt_pk_bf16_f32 v95, v56, v60
	v_cvt_pk_bf16_f32 v96, v64, v68
	v_cvt_pk_bf16_f32 v97, v72, v76
	v_cvt_pk_bf16_f32 v98, v49, v53
	v_cvt_pk_bf16_f32 v99, v57, v61
	v_cvt_pk_bf16_f32 v100, v65, v69
	v_cvt_pk_bf16_f32 v101, v73, v77
	global_store_dwordx4 v45, v[86:89], s[24:25] sc1
	v_add_u32_e32 v45, s41, v45
	global_store_dwordx4 v45, v[90:93], s[24:25] sc1
	v_add_u32_e32 v45, s41, v45
	global_store_dwordx4 v45, v[94:97], s[24:25] sc1
	v_add_u32_e32 v45, s41, v45
	global_store_dwordx4 v45, v[98:101], s[24:25] sc1
	s_branch .Lsl_in_loop
.Lsl_in_single:
	s_waitcnt vmcnt(0)
	s_cmp_eq_u32 s43, 0
	s_cbranch_scc1 .Lsl_in_nmul11
	v_mul_f32_e32 v2, v2, v34
	v_mul_f32_e32 v3, v3, v34
	v_mul_f32_e32 v4, v4, v34
	v_mul_f32_e32 v5, v5, v34
	v_mul_f32_e32 v6, v6, v35
	v_mul_f32_e32 v7, v7, v35
	v_mul_f32_e32 v8, v8, v35
	v_mul_f32_e32 v9, v9, v35
	v_mul_f32_e32 v10, v10, v36
	v_mul_f32_e32 v11, v11, v36
	v_mul_f32_e32 v12, v12, v36
	v_mul_f32_e32 v13, v13, v36
	v_mul_f32_e32 v14, v14, v37
	v_mul_f32_e32 v15, v15, v37
	v_mul_f32_e32 v16, v16, v37
	v_mul_f32_e32 v17, v17, v37
	v_mul_f32_e32 v18, v18, v38
	v_mul_f32_e32 v19, v19, v38
	v_mul_f32_e32 v20, v20, v38
	v_mul_f32_e32 v21, v21, v38
	v_mul_f32_e32 v22, v22, v39
	v_mul_f32_e32 v23, v23, v39
	v_mul_f32_e32 v24, v24, v39
	v_mul_f32_e32 v25, v25, v39
	v_mul_f32_e32 v26, v26, v40
	v_mul_f32_e32 v27, v27, v40
	v_mul_f32_e32 v28, v28, v40
	v_mul_f32_e32 v29, v29, v40
	v_mul_f32_e32 v30, v30, v41
	v_mul_f32_e32 v31, v31, v41
	v_mul_f32_e32 v32, v32, v41
	v_mul_f32_e32 v33, v33, v41
.Lsl_in_nmul11:
	v_cvt_pk_bf16_f32 v86, v2, v6
	v_cvt_pk_bf16_f32 v87, v10, v14
	v_cvt_pk_bf16_f32 v88, v18, v22
	v_cvt_pk_bf16_f32 v89, v26, v30
	v_cvt_pk_bf16_f32 v90, v3, v7
	v_cvt_pk_bf16_f32 v91, v11, v15
	v_cvt_pk_bf16_f32 v92, v19, v23
	v_cvt_pk_bf16_f32 v93, v27, v31
	v_cvt_pk_bf16_f32 v94, v4, v8
	v_cvt_pk_bf16_f32 v95, v12, v16
	v_cvt_pk_bf16_f32 v96, v20, v24
	v_cvt_pk_bf16_f32 v97, v28, v32
	v_cvt_pk_bf16_f32 v98, v5, v9
	v_cvt_pk_bf16_f32 v99, v13, v17
	v_cvt_pk_bf16_f32 v100, v21, v25
	v_cvt_pk_bf16_f32 v101, v29, v33
	global_store_dwordx4 v44, v[86:89], s[24:25] sc1
	v_add_u32_e32 v44, s41, v44
	global_store_dwordx4 v44, v[90:93], s[24:25] sc1
	v_add_u32_e32 v44, s41, v44
	global_store_dwordx4 v44, v[94:97], s[24:25] sc1
	v_add_u32_e32 v44, s41, v44
	global_store_dwordx4 v44, v[98:101], s[24:25] sc1
.Lsl_in_next:
	s_add_i32 s28, s28, 1
	s_branch .Lsl_in_dispatch

;     ...
;     for (int mi = 0; mi < 7 * DEPTH; ++mi) {
;         if (!((mask >> mi) & 1u)) continue;
;         const int l = mi / 7, kind = mi - 7 * l;
;         const float* W; const float* ks = nullptr; bf16_t* WT; int K, N, rm = 0;
;         if (kind == 0)      { W = a.in[2] + (size_t)l * 2048 * 7680;  K = 2048; N = 7680; WT = (bf16_t*)(ws + WS_WIN + l * SZ_WIN); ks = a.in[1] + l * 2048; rm = 3; }
;         else if (kind == 1) { W = a.in[10] + (size_t)l * 1024 * 2048; K = 1024; N = 2048; WT = (bf16_t*)(ws + WS_WA + l * SZ_WA); }
;         else if (kind == 2) { W = a.in[11] + (size_t)l * 1024 * 2048; K = 1024; N = 2048; WT = (bf16_t*)(ws + WS_WB + l * SZ_WB); }
;         else if (kind == 3) { W = a.in[12] + (size_t)l * 2048 * 2048; K = 2048; N = 2048; WT = (bf16_t*)(ws + WS_WO + l * SZ_WO); }
;         else if (kind == 4) { W = a.in[14] + (size_t)l * 2048 * 5632; K = 2048; N = 5632; WT = (bf16_t*)(ws + WS_WGU + l * SZ_WGU); ks = a.in[13] + l * 2048; rm = 1; }
;         else if (kind == 5) { W = a.in[15] + (size_t)l * 2048 * 5632; K = 2048; N = 5632; WT = (bf16_t*)(ws + WS_WGU + l * SZ_WGU); ks = a.in[13] + l * 2048; rm = 2; }
;         else                { W = a.in[16] + (size_t)l * 5632 * 2048; K = 5632; N = 2048; WT = (bf16_t*)(ws + WS_WD + l * SZ_WD); }
;         const int nitems = (K >> 6) * (N >> 5);
;         int ilo = 0, ihi = nitems; if ((fmask >> mi) & 1u) { ilo = (nitems * flo) >> 4; ihi = (nitems * fhi) >> 4; }
;         const int cnt = ihi - ilo;
;         int first = (gw - base) % NGW; if (first < 0) first += NGW;
;         for (int it = first; it < cnt; it += NGW) tr_item(W, K, N, WT, ks, rm, ilo + it, lane);
;         base = (base + cnt) % NGW;
; __global__ void __launch_bounds__(NTHREADS, 2) mk_fwd(Args args) {
;     ...
;             { int thr = S.nwg - ((S.nwg + G - 1) / G - 1) * G; if (thr >= G) thr = 0;
;                 if (blk >= thr) p0_prologue(args, (blk - thr) * NWAVES + wave, (G - thr) * NWAVES, lane, l == 0 ? 0x07C0u : 0x2000u, false); }
.LBB0_670:
	v_readlane_b32 s6, v248, 44
	v_readlane_b32 s7, v248, 45
	s_andn2_b64 vcc, exec, s[6:7]
	s_cbranch_vccnz .LBB0_716
	s_cmpk_lg_u32 s3, 0x100
	s_cbranch_scc1 .Lslot_gu_orig
	v_readfirstlane_b32 s2, v204
	v_and_b32_e32 v43, 63, v204
	v_lshrrev_b32_e32 v102, 3, v43
	v_and_b32_e32 v103, 7, v43
	s_lshr_b32 s2, s2, 6
	s_sub_i32 s19, s85, 128
	s_lshl_b32 s19, s19, 3
	s_add_i32 s2, s2, s19
	v_lshlrev_b32_e32 v110, 5, v102
	s_mov_b32 s28, 0
	s_cmp_lg_u32 s64, 0
	s_cselect_b32 s28, 16, 0
.Lsl_gu_dispatch:
	s_cmp_eq_u32 s28, 0
	s_cbranch_scc1 .Lsl_gu_set0
	s_cmp_eq_u32 s28, 1
	s_cbranch_scc1 .Lsl_gu_set1
	s_cmp_eq_u32 s28, 16
	s_cbranch_scc1 .Lsl_gu_set16
	s_branch .LBB0_716
.Lsl_gu_set0:
	s_mov_b64 s[22:23], s[88:89]
	v_readlane_b32 s24, v250, 36
	v_readlane_b32 s25, v250, 37
	v_mul_u32_u24_e32 v104, 0x10000, v102
	v_lshl_add_u32 v104, v103, 4, v104
	v_mul_u32_u24_e32 v105, 0xb000, v103
	v_lshl_add_u32 v105, v102, 4, v105
	s_add_u32 s24, s24, 0xb5c0000
	s_addc_u32 s25, s25, 0
	s_mov_b32 s36, 0x2000
	s_mov_b32 s37, 0x80000
	s_movk_i32 s38, 1
	s_mov_b32 s39, 6
	s_movk_i32 s40, 64
	s_movk_i32 s41, 0x2c00
	s_mov_b32 s42, 0
	s_mov_b32 s43, 0
	s_movk_i32 s44, 0
	s_movk_i32 s29, 5632
	s_sub_i32 s4, s2, 0
	s_and_b32 s4, s4, 1023
	s_branch .Lsl_gu_loop
.Lsl_gu_set1:
	v_readlane_b32 s22, v250, 6
	v_readlane_b32 s23, v250, 7
	v_readlane_b32 s24, v250, 36
	v_readlane_b32 s25, v250, 37
	v_readlane_b32 s26, v250, 4
	v_readlane_b32 s27, v250, 5
	v_mul_u32_u24_e32 v104, 0x3c000, v102
	v_lshl_add_u32 v104, v103, 4, v104
	v_mul_u32_u24_e32 v105, 0x4000, v103
	v_lshl_add_u32 v105, v102, 4, v105
	s_add_u32 s22, s22, 0x3c00000
	s_addc_u32 s23, s23, 0
	s_add_u32 s24, s24, 0x1fc0000
	s_addc_u32 s25, s25, 0
	s_add_u32 s26, s26, 0x2000
	s_addc_u32 s27, s27, 0
	s_mov_b32 s36, 0x7800
	s_mov_b32 s37, 0x1e0000
	s_movk_i32 s38, 8739
	s_mov_b32 s39, 21
	s_movk_i32 s40, 240
	s_movk_i32 s41, 0x1000
	s_mov_b32 s42, 3
	s_mov_b32 s43, 1
	s_movk_i32 s44, 0
	s_movk_i32 s29, 7680
	s_sub_i32 s4, s2, 512
	s_and_b32 s4, s4, 1023
	s_branch .Lsl_gu_loop
.Lsl_gu_set16:
	s_mov_b64 s[22:23], s[88:89]
	v_readlane_b32 s24, v250, 36
	v_readlane_b32 s25, v250, 37
	v_mul_u32_u24_e32 v104, 0x10000, v102
	v_lshl_add_u32 v104, v103, 4, v104
	v_mul_u32_u24_e32 v105, 0xb000, v103
	v_lshl_add_u32 v105, v102, 4, v105
	s_add_u32 s22, s22, 0x2c00000
	s_addc_u32 s23, s23, 0
	s_add_u32 s24, s24, 0xcbc0000
	s_addc_u32 s25, s25, 0
	s_mov_b32 s36, 0x2000
	s_mov_b32 s37, 0x80000
	s_movk_i32 s38, 1
	s_mov_b32 s39, 6
	s_movk_i32 s40, 64
	s_movk_i32 s41, 0x2c00
	s_mov_b32 s42, 0
	s_mov_b32 s43, 0
	s_movk_i32 s44, 0
	s_movk_i32 s29, 5632
	s_sub_i32 s4, s2, 0
	s_and_b32 s4, s4, 1023
	s_branch .Lsl_gu_loop

; __device__ __forceinline__ void tr_item(const float* __restrict__ W, int K, int N, bf16_t* WT, const float* __restrict__ kscale, int rowmode, int item, int lane) {
;     const int nblk = N >> 5, kb = item / nblk, nb = item - kb * nblk;
;     const int c = lane >> 3, q = lane & 7, k0 = kb * 64 + c * 8, n0 = nb * 32 + q * 4;
;     f32x4 v[8];
; #pragma unroll
;     for (int i = 0; i < 8; ++i) v[i] = __builtin_nontemporal_load((const f32x4*)(W + (size_t)(k0 + i) * N + n0));
;     if (kscale) { const f32x4 s0 = *(const f32x4*)(kscale + k0), s1 = *(const f32x4*)(kscale + k0 + 4);
; #pragma unroll
;         for (int i = 0; i < 4; ++i) { v[i] = v[i] * s0[i]; v[4 + i] = v[4 + i] * s1[i]; } }
;     int drow;
;     if (rowmode == 0) drow = n0;
;     else if (rowmode == 3) { const int g = n0 - pg8::C_GA; drow = g < 0 ? n0 : pg8::C_GA + (((g & 2047) >> 7) << 8) + ((g >> 11) << 7) + (g & 127); }
;     else drow = ((n0 >> 7) << 8) + (n0 & 127) + (rowmode == 2 ? 128 : 0);
.Lsl_gu_rmd2:
	s_mul_i32 s19, s19, s41
	s_lshl_b32 s20, s17, 7
	s_add_i32 s19, s19, s20
	v_add_u32_e32 v44, s19, v105
	s_add_i32 s4, s4, 1024
	s_cmp_ge_u32 s4, s29
	s_cbranch_scc1 .Lsl_gu_single
	s_add_i32 s16, s4, s44
	s_mul_i32 s17, s16, s38
	s_lshr_b32 s17, s17, s39
	s_mul_i32 s19, s17, s40
	s_sub_i32 s18, s16, s19
	s_mul_i32 s19, s17, s37
	s_lshl_b32 s20, s18, 7
	s_add_i32 s19, s19, s20
	v_add_u32_e32 v42, s19, v104
	s_cmp_eq_u32 s43, 0
	s_cbranch_scc1 .Lsl_gu_nks4
	s_lshl_b32 s19, s17, 8
	v_add_u32_e32 v43, s19, v110
	global_load_dwordx4 v[78:81], v43, s[26:27]
	global_load_dwordx4 v[82:85], v43, s[26:27] offset:16

; __device__ __forceinline__ unsigned cvt_pk_bf16(float lo, float hi) { unsigned r; asm volatile("v_cvt_pk_bf16_f32 %0, %1, %2" : "=v"(r) : "v"(lo), "v"(hi)); return r; }
; __device__ __forceinline__ void st16_wt(void* p, u32x4 v) { asm volatile("global_store_dwordx4 %0, %1, off sc1\n\ts_nop 1" :: "v"(p), "v"(v) : "memory"); }
; __device__ __forceinline__ void tr_item(const float* __restrict__ W, int K, int N, bf16_t* WT, const float* __restrict__ kscale, int rowmode, int item, int lane) {
;     ...
;     else drow = ((n0 >> 7) << 8) + (n0 & 127) + (rowmode == 2 ? 128 : 0);
; #pragma unroll
;     for (int e = 0; e < 4; ++e) { u32x4 o; o.x = cvt_pk_bf16(v[0][e], v[1][e]); o.y = cvt_pk_bf16(v[2][e], v[3][e]); o.z = cvt_pk_bf16(v[4][e], v[5][e]); o.w = cvt_pk_bf16(v[6][e], v[7][e]);
;         pg8::st16_wt(WT + (size_t)(drow + e) * K + k0, o); }
.Lsl_gu_rmd5:
	s_mul_i32 s19, s19, s41
	s_lshl_b32 s20, s17, 7
	s_add_i32 s19, s19, s20
	v_add_u32_e32 v45, s19, v105
	s_add_i32 s4, s4, 1024
	s_cmp_eq_u32 s43, 0
	s_cbranch_scc1 .Lsl_gu_w87
	s_waitcnt vmcnt(10)
	s_branch .Lsl_gu_wd8
